# v31 + grid barrier: every waiter polls the cross-XCD arrival counter itself (no separate release-generation hop)
# baseline (speedup 1.0000x reference)
; __device__ __forceinline__ unsigned xb_ld(unsigned* p)              { return __hip_atomic_load(p, __ATOMIC_RELAXED, __HIP_MEMORY_SCOPE_AGENT); }
; __device__ __forceinline__ unsigned xb_add(unsigned* p, unsigned v) { return __hip_atomic_fetch_add(p, v, __ATOMIC_RELAXED, __HIP_MEMORY_SCOPE_AGENT); }
; #define XB_SPIN(cond, bar) do { unsigned _sp = 0; while (cond) { __builtin_amdgcn_s_sleep(1); \
;     if ((++_sp & 255u) == 0u) { if (xb_ld(&(bar)[XB_TMO])) break; if (_sp > XB_SPIN_CAP) { atomicAdd(&(bar)[XB_TMO], 1u); break; } } } } while (0)
; __device__ __forceinline__ void xcd_barrier(const XcdBarrier& b) {
;     ...
;     if (threadIdx.x == 0) {
;         unsigned* bar = b.bar;
;         __builtin_amdgcn_s_waitcnt(0);
;         unsigned nloc = b.st[0], nx = b.st[1];
;         if (nloc == 0u) { xcd_barrier_complete(bar, b.x, nloc, nx); b.st[0] = nloc; b.st[1] = nx; }
;         const unsigned old = xb_add(&bar[XB_XSUB(b.x)], 1u);
;         const unsigned gen = old / nloc;
;         if (old + 1u == (gen + 1u) * nloc) {
;             __builtin_amdgcn_fence(__ATOMIC_RELEASE, "agent");
;             asm volatile("s_waitcnt vmcnt(0)" ::: "memory");
;             const unsigned og = xb_add(&bar[XB_TOP], 1u);
;             const unsigned tg = og / nx;
;             if (og + 1u == (tg + 1u) * nx) xb_add(&bar[XB_TOPGEN], 1u);
;             else XB_SPIN(xb_ld(&bar[XB_TOPGEN]) == tg, bar);
;             __builtin_amdgcn_fence(__ATOMIC_ACQUIRE, "agent");
;             xb_add(&bar[XB_XGEN(b.x)], 1u);
;             asm volatile("s_waitcnt vmcnt(0)" ::: "memory");
;         } else {
;             XB_SPIN(xb_ld(&bar[XB_XGEN(b.x)]) == gen, bar);
.LBB0_877:
	v_readlane_b32 s2, v249, 12
	v_readlane_b32 s3, v249, 13
	s_nop 1
	v_mov_b64_e32 v[180:181], s[2:3]
	v_readlane_b32 s2, v249, 26
	s_waitcnt vmcnt(0) expcnt(0) lgkmcnt(0)
	s_nop 0
	v_mov_b32_e32 v1, s2
	ds_read_b32 v3, v1
	v_readlane_b32 s2, v249, 27
	s_waitcnt lgkmcnt(0)
	v_cmp_ne_u32_e32 vcc, 0, v3
	v_mov_b32_e32 v1, s2
	ds_read_b32 v2, v1
	s_cbranch_vccnz .LBB0_892
	s_mov_b32 s2, 1
	s_branch .LBB0_880

; __device__ __forceinline__ unsigned xb_ld(unsigned* p)              { return __hip_atomic_load(p, __ATOMIC_RELAXED, __HIP_MEMORY_SCOPE_AGENT); }
; __device__ __forceinline__ unsigned xb_add(unsigned* p, unsigned v) { return __hip_atomic_fetch_add(p, v, __ATOMIC_RELAXED, __HIP_MEMORY_SCOPE_AGENT); }
; #define XB_SPIN(cond, bar) do { unsigned _sp = 0; while (cond) { __builtin_amdgcn_s_sleep(1); \
;     if ((++_sp & 255u) == 0u) { if (xb_ld(&(bar)[XB_TMO])) break; if (_sp > XB_SPIN_CAP) { atomicAdd(&(bar)[XB_TMO], 1u); break; } } } } while (0)
; __device__ __forceinline__ void xcd_barrier(const XcdBarrier& b) {
;     ...
;         const unsigned old = xb_add(&bar[XB_XSUB(b.x)], 1u);
;         const unsigned gen = old / nloc;
;         if (old + 1u == (gen + 1u) * nloc) {
;             __builtin_amdgcn_fence(__ATOMIC_RELEASE, "agent");
;             asm volatile("s_waitcnt vmcnt(0)" ::: "memory");
;             const unsigned og = xb_add(&bar[XB_TOP], 1u);
;             const unsigned tg = og / nx;
;             if (og + 1u == (tg + 1u) * nx) xb_add(&bar[XB_TOPGEN], 1u);
;             else XB_SPIN(xb_ld(&bar[XB_TOPGEN]) == tg, bar);
;             __builtin_amdgcn_fence(__ATOMIC_ACQUIRE, "agent");
;             xb_add(&bar[XB_XGEN(b.x)], 1u);
;             asm volatile("s_waitcnt vmcnt(0)" ::: "memory");
;         } else {
;             XB_SPIN(xb_ld(&bar[XB_XGEN(b.x)]) == gen, bar);
.LBB0_892:
	global_atomic_add v4, v[178:179], v201, off sc0
	v_cvt_f32_u32_e32 v1, v3
	v_sub_u32_e32 v5, 0, v3
	v_rcp_iflag_f32_e32 v1, v1
	s_nop 0
	v_mul_f32_e32 v1, 0x4f7ffffe, v1
	v_cvt_u32_f32_e32 v1, v1
	v_mul_lo_u32 v5, v5, v1
	v_mul_hi_u32 v5, v1, v5
	v_add_u32_e32 v1, v1, v5
	s_waitcnt vmcnt(0)
	v_mul_hi_u32 v1, v4, v1
	v_mul_lo_u32 v5, v1, v3
	v_sub_u32_e32 v5, v4, v5
	v_add_u32_e32 v6, 1, v1
	v_cmp_ge_u32_e32 vcc, v5, v3
	v_add_u32_e32 v4, 1, v4
	s_nop 0
	v_cndmask_b32_e32 v1, v1, v6, vcc
	v_sub_u32_e32 v6, v5, v3
	v_cndmask_b32_e32 v5, v5, v6, vcc
	v_add_u32_e32 v6, 1, v1
	v_cmp_ge_u32_e32 vcc, v5, v3
	s_nop 1
	v_cndmask_b32_e32 v1, v1, v6, vcc
	v_mul_lo_u32 v5, v3, v1
	v_add_u32_e32 v3, v5, v3
	v_cmp_ne_u32_e32 vcc, v4, v3
	s_and_saveexec_b64 s[2:3], vcc
	s_xor_b64 s[6:7], exec, s[2:3]
	s_cbranch_execz .LBB0_906
	s_waitcnt lgkmcnt(0)
	v_add_u32_e32 v6, 1, v1
	v_mul_lo_u32 v6, v6, v2
	global_load_dword v2, v[180:181], off sc1
	s_waitcnt vmcnt(0)
	v_cmp_lt_u32_e32 vcc, v2, v6
	s_and_saveexec_b64 s[8:9], vcc
	s_cbranch_execz .LBB0_905
	s_mov_b32 s2, 1
	s_mov_b64 s[10:11], 0
	s_branch .LBB0_896

; __device__ __forceinline__ unsigned xb_ld(unsigned* p)              { return __hip_atomic_load(p, __ATOMIC_RELAXED, __HIP_MEMORY_SCOPE_AGENT); }
; #define XB_SPIN(cond, bar) do { unsigned _sp = 0; while (cond) { __builtin_amdgcn_s_sleep(1); \
;     if ((++_sp & 255u) == 0u) { if (xb_ld(&(bar)[XB_TMO])) break; if (_sp > XB_SPIN_CAP) { atomicAdd(&(bar)[XB_TMO], 1u); break; } } } } while (0)
; __device__ __forceinline__ void xcd_barrier(const XcdBarrier& b) {
;     ...
;             XB_SPIN(xb_ld(&bar[XB_XGEN(b.x)]) == gen, bar);
.LBB0_900:
	global_load_dword v2, v[180:181], off sc1
	s_add_i32 s2, s2, 1
	s_mov_b64 s[16:17], -1
	s_waitcnt vmcnt(0)
	v_cmp_ge_u32_e32 vcc, v2, v6
	s_orn2_b64 s[14:15], vcc, exec
	s_branch .LBB0_895

; __device__ __forceinline__ unsigned xb_ld(unsigned* p)              { return __hip_atomic_load(p, __ATOMIC_RELAXED, __HIP_MEMORY_SCOPE_AGENT); }
; __device__ __forceinline__ unsigned xb_add(unsigned* p, unsigned v) { return __hip_atomic_fetch_add(p, v, __ATOMIC_RELAXED, __HIP_MEMORY_SCOPE_AGENT); }
; #define XB_SPIN(cond, bar) do { unsigned _sp = 0; while (cond) { __builtin_amdgcn_s_sleep(1); \
;     if ((++_sp & 255u) == 0u) { if (xb_ld(&(bar)[XB_TMO])) break; if (_sp > XB_SPIN_CAP) { atomicAdd(&(bar)[XB_TMO], 1u); break; } } } } while (0)
; __device__ __forceinline__ void xcd_barrier(const XcdBarrier& b) {
;     ...
;         const unsigned old = xb_add(&bar[XB_XSUB(b.x)], 1u);
;         const unsigned gen = old / nloc;
;         if (old + 1u == (gen + 1u) * nloc) {
;             __builtin_amdgcn_fence(__ATOMIC_RELEASE, "agent");
;             asm volatile("s_waitcnt vmcnt(0)" ::: "memory");
;             const unsigned og = xb_add(&bar[XB_TOP], 1u);
;             const unsigned tg = og / nx;
;             if (og + 1u == (tg + 1u) * nx) xb_add(&bar[XB_TOPGEN], 1u);
;             else XB_SPIN(xb_ld(&bar[XB_TOPGEN]) == tg, bar);
;             __builtin_amdgcn_fence(__ATOMIC_ACQUIRE, "agent");
;             xb_add(&bar[XB_XGEN(b.x)], 1u);
;             asm volatile("s_waitcnt vmcnt(0)" ::: "memory");
;         } else {
;             XB_SPIN(xb_ld(&bar[XB_XGEN(b.x)]) == gen, bar);
.LBB0_909:
	s_or_b64 exec, exec, s[8:9]
	s_waitcnt vmcnt(0)
	v_readfirstlane_b32 s2, v3
	v_sub_u32_e32 v4, 0, v2
	s_mov_b64 s[8:9], -1
	v_add_u32_e32 v3, s2, v1
	v_cvt_f32_u32_e32 v1, v2
	v_readlane_b32 s2, v249, 14
	v_readlane_b32 s3, v249, 15
	v_rcp_iflag_f32_e32 v1, v1
	s_nop 0
	v_mul_f32_e32 v1, 0x4f7ffffe, v1
	v_cvt_u32_f32_e32 v1, v1
	v_mul_lo_u32 v4, v4, v1
	v_mul_hi_u32 v4, v1, v4
	v_add_u32_e32 v1, v1, v4
	v_mul_hi_u32 v1, v3, v1
	v_mul_lo_u32 v4, v1, v2
	v_sub_u32_e32 v4, v3, v4
	v_cmp_ge_u32_e32 vcc, v4, v2
	v_add_u32_e32 v5, 1, v1
	v_add_u32_e32 v3, 1, v3
	v_cndmask_b32_e32 v1, v1, v5, vcc
	v_sub_u32_e32 v5, v4, v2
	v_cndmask_b32_e32 v4, v4, v5, vcc
	v_cmp_ge_u32_e32 vcc, v4, v2
	v_add_u32_e32 v4, 1, v1
	s_nop 0
	v_cndmask_b32_e32 v1, v1, v4, vcc
	v_mul_lo_u32 v4, v2, v1
	v_add_u32_e32 v2, v4, v2
	v_mov_b32_e32 v6, v2
	v_cmp_ne_u32_e32 vcc, v3, v2
	v_mov_b64_e32 v[2:3], s[2:3]
	s_and_saveexec_b64 s[6:7], vcc
	s_cbranch_execz .LBB0_922
	v_readlane_b32 s2, v249, 12
	v_readlane_b32 s3, v249, 13
	s_mov_b64 s[10:11], 0
	s_nop 3
	global_load_dword v2, v175, s[2:3] sc1
	s_waitcnt vmcnt(0)
	v_cmp_lt_u32_e32 vcc, v2, v6
	s_and_saveexec_b64 s[8:9], vcc
	s_cbranch_execz .LBB0_921
	s_mov_b32 s2, 1
	s_branch .LBB0_913

; __device__ __forceinline__ unsigned xb_ld(unsigned* p)              { return __hip_atomic_load(p, __ATOMIC_RELAXED, __HIP_MEMORY_SCOPE_AGENT); }
; #define XB_SPIN(cond, bar) do { unsigned _sp = 0; while (cond) { __builtin_amdgcn_s_sleep(1); \
;     if ((++_sp & 255u) == 0u) { if (xb_ld(&(bar)[XB_TMO])) break; if (_sp > XB_SPIN_CAP) { atomicAdd(&(bar)[XB_TMO], 1u); break; } } } } while (0)
; __device__ __forceinline__ void xcd_barrier(const XcdBarrier& b) {
;     ...
;             else XB_SPIN(xb_ld(&bar[XB_TOPGEN]) == tg, bar);
.LBB0_917:
	v_readlane_b32 s14, v249, 12
	v_readlane_b32 s15, v249, 13
	s_add_i32 s2, s2, 1
	s_mov_b64 s[16:17], -1
	s_nop 2
	global_load_dword v2, v175, s[14:15] sc1
	s_waitcnt vmcnt(0)
	v_cmp_ge_u32_e32 vcc, v2, v6
	s_orn2_b64 s[14:15], vcc, exec
	s_branch .LBB0_912
